# non-temporal hint also on the combine-pass loads and the down-projection residual loads
# baseline (speedup 1.0000x reference)
; __device__ __forceinline__ unsigned cvt_pk_bf16(float lo, float hi) { unsigned r; asm volatile("v_cvt_pk_bf16_f32 %0, %1, %2" : "=v"(r) : "v"(lo), "v"(hi)); return r; }
; __device__ __forceinline__ float bf_lo(unsigned w) { return __uint_as_float(w << 16); }
; __device__ __forceinline__ float bf_hi(unsigned w) { return __uint_as_float(w & 0xffff0000u); }
; __device__ __forceinline__ void combine_row(int row, const float (&y)[8], const float* SSQNA, bf16_t* YCAT, int lane) {
;     float s = 0.f;
; #pragma unroll
;     for (int j = 0; j < 8; ++j) s += y[j] * y[j];
;     s = wave_sum(s);
;     const float rstd = 1.0f / sqrtf(s * (1.0f / 512.0f) + EPS);
;     u32x4 o; o.x = cvt_pk_bf16(y[0] * rstd, y[1] * rstd); o.y = cvt_pk_bf16(y[2] * rstd, y[3] * rstd); o.z = cvt_pk_bf16(y[4] * rstd, y[5] * rstd); o.w = cvt_pk_bf16(y[6] * rstd, y[7] * rstd);
;     *(u32x4*)(YCAT + (size_t)row * DM + lane * 8) = o;
;     float t = SSQNA[(size_t)row * 8 + (lane & 7)]; t += __shfl_xor(t, 1); t += __shfl_xor(t, 2); t += __shfl_xor(t, 4);
;     const float rn = 1.0f / sqrtf(t * (1.0f / 512.0f) + EPS);
;     u32x4* ap = (u32x4*)(YCAT + (size_t)row * DM + 512 + lane * 8); const u32x4 aw = *ap; u32x4 ow;
; #pragma unroll
;     for (int j = 0; j < 4; ++j) ow[j] = cvt_pk_bf16(bf_lo(aw[j]) * rn, bf_hi(aw[j]) * rn);
;     *ap = ow;
; }
.LBB0_405:
	s_or_b64 exec, exec, s[6:7]
	v_pk_add_f32 v[0:1], v[20:21], v[28:29] neg_lo:[0,1] neg_hi:[0,1]
	v_pk_add_f32 v[2:3], v[22:23], v[30:31] neg_lo:[0,1] neg_hi:[0,1]
	v_pk_mul_f32 v[20:21], v[0:1], v[0:1]
	v_pk_mul_f32 v[22:23], v[2:3], v[2:3]
	v_add_f32_e32 v10, v20, v21
	v_pk_add_f32 v[4:5], v[24:25], v[32:33] neg_lo:[0,1] neg_hi:[0,1]
	v_add_f32_e32 v10, v22, v10
	v_pk_mul_f32 v[24:25], v[4:5], v[4:5]
	v_add_f32_e32 v10, v23, v10
	v_pk_add_f32 v[6:7], v[26:27], v[34:35] neg_lo:[0,1] neg_hi:[0,1]
	v_add_f32_e32 v10, v24, v10
	v_pk_mul_f32 v[26:27], v[6:7], v[6:7]
	v_add_f32_e32 v10, v25, v10
	v_add_f32_e32 v10, v26, v10
	v_add_f32_e32 v10, v27, v10
	ds_bpermute_b32 v20, v47, v10
	v_lshlrev_b32_e32 v24, 11, v59
	s_add_i32 s10, s10, s11
	s_waitcnt lgkmcnt(0)
	v_add_f32_e32 v10, v10, v20
	ds_bpermute_b32 v20, v48, v10
	s_waitcnt lgkmcnt(0)
	v_add_f32_e32 v10, v10, v20
	ds_bpermute_b32 v20, v49, v10
	s_waitcnt lgkmcnt(0)
	v_add_f32_e32 v10, v10, v20
	ds_bpermute_b32 v20, v50, v10
	s_waitcnt lgkmcnt(0)
	v_add_f32_e32 v10, v10, v20
	ds_bpermute_b32 v20, v51, v10
	s_waitcnt lgkmcnt(0)
	v_add_f32_e32 v10, v10, v20
	ds_bpermute_b32 v20, v52, v10
	s_waitcnt lgkmcnt(0)
	v_add_f32_e32 v10, v10, v20
	v_fmamk_f32 v10, v10, 0x3b000000, v55
	v_mul_f32_e32 v20, 0x4f800000, v10
	v_cmp_gt_f32_e32 vcc, s33, v10
	s_nop 1
	v_cndmask_b32_e32 v10, v10, v20, vcc
	v_sqrt_f32_e32 v22, v10
	v_or_b32_e32 v20, v24, v58
	v_ashrrev_i32_e32 v21, 31, v20
	v_add_u32_e32 v23, -1, v22
	v_add_u32_e32 v25, 1, v22
	v_fma_f32 v26, -v23, v22, v10
	v_fma_f32 v27, -v25, v22, v10
	v_cmp_ge_f32_e64 s[6:7], 0, v26
	s_nop 1
	v_cndmask_b32_e64 v22, v22, v23, s[6:7]
	v_cmp_lt_f32_e64 s[6:7], 0, v27
	s_nop 1
	v_cndmask_b32_e64 v22, v22, v25, s[6:7]
	v_mul_f32_e32 v23, 0x37800000, v22
	v_cndmask_b32_e32 v22, v22, v23, vcc
	v_cmp_class_f32_e32 vcc, v10, v56
	s_nop 1
	v_cndmask_b32_e32 v10, v22, v10, vcc
	v_div_scale_f32 v25, s[6:7], v10, v10, 1.0
	v_rcp_f32_e32 v26, v25
	v_div_scale_f32 v27, vcc, 1.0, v10, 1.0
	v_lshlrev_b64 v[22:23], 11, v[20:21]
	v_fma_f32 v28, -v25, v26, 1.0
	v_fmac_f32_e32 v26, v28, v26
	v_mul_f32_e32 v28, v27, v26
	v_fma_f32 v29, -v25, v28, v27
	v_fmac_f32_e32 v28, v29, v26
	v_fma_f32 v25, -v25, v28, v27
	v_div_fmas_f32 v25, v25, v26, v28
	v_div_fixup_f32 v10, v25, v10, 1.0
	v_mul_f32_e32 v0, v0, v10
	v_mul_f32_e32 v1, v1, v10
	v_mul_f32_e32 v2, v2, v10
	v_mul_f32_e32 v4, v4, v10
	v_mul_f32_e32 v5, v5, v10
	v_mul_f32_e32 v3, v3, v10
	v_cvt_pk_bf16_f32 v0, v0, v1
	v_cvt_pk_bf16_f32 v1, v2, v3
	v_cvt_pk_bf16_f32 v2, v4, v5
	v_lshl_add_u64 v[4:5], v[16:17], 0, v[22:23]
	v_mul_f32_e32 v6, v6, v10
	v_mul_f32_e32 v7, v7, v10
	v_cvt_pk_bf16_f32 v3, v6, v7
	global_store_dwordx4 v[4:5], v[0:3], off sc1
	v_mul_f32_e32 v6, v43, v43
	v_fmac_f32_e32 v6, v42, v42
	v_lshlrev_b64 v[0:1], 5, v[20:21]
	v_lshl_add_u64 v[0:1], v[14:15], 0, v[0:1]
	global_load_dword v7, v[0:1], off
	v_fmac_f32_e32 v6, v40, v40
	v_fmac_f32_e32 v6, v41, v41
	v_fmac_f32_e32 v6, v38, v38
	v_fmac_f32_e32 v6, v39, v39
	v_fmac_f32_e32 v6, v36, v36
	v_fmac_f32_e32 v6, v37, v37
	ds_bpermute_b32 v10, v47, v6
	global_load_dwordx4 v[0:3], v[4:5], off offset:1024 nt
	s_waitcnt lgkmcnt(0)
	v_add_f32_e32 v6, v6, v10
	ds_bpermute_b32 v10, v48, v6
	s_waitcnt lgkmcnt(0)
	v_add_f32_e32 v6, v6, v10
	ds_bpermute_b32 v10, v49, v6
	s_waitcnt lgkmcnt(0)
	v_add_f32_e32 v6, v6, v10
	ds_bpermute_b32 v10, v50, v6
	s_waitcnt lgkmcnt(0)
	v_add_f32_e32 v6, v6, v10
	ds_bpermute_b32 v10, v51, v6
	s_waitcnt lgkmcnt(0)
	v_add_f32_e32 v6, v6, v10
	ds_bpermute_b32 v10, v52, v6
	s_waitcnt lgkmcnt(0)
	v_add_f32_e32 v6, v6, v10
	v_fmamk_f32 v6, v6, 0x3b000000, v55
	v_mul_f32_e32 v10, 0x4f800000, v6
	v_cmp_gt_f32_e32 vcc, s33, v6
	s_waitcnt vmcnt(0)
	v_lshlrev_b32_e32 v26, 16, v2
	v_cndmask_b32_e32 v10, v6, v10, vcc
	v_sqrt_f32_e32 v20, v10
	v_sub_u32_e32 v6, 0x800, v58
	v_cndmask_b32_e64 v6, v6, v57, s[4:5]
	v_add_u32_e32 v6, v6, v24
	v_add_u32_e32 v21, -1, v20
	v_add_u32_e32 v22, 1, v20
	v_fma_f32 v23, -v21, v20, v10
	v_fma_f32 v24, -v22, v20, v10
	v_cmp_ge_f32_e64 s[4:5], 0, v23
	v_and_b32_e32 v2, 0xffff0000, v2
	v_lshlrev_b32_e32 v27, 16, v3
	v_cndmask_b32_e64 v20, v20, v21, s[4:5]
	v_cmp_lt_f32_e64 s[4:5], 0, v24
	v_and_b32_e32 v3, 0xffff0000, v3
	s_nop 0
	v_cndmask_b32_e64 v20, v20, v22, s[4:5]
	ds_bpermute_b32 v22, v47, v7
	v_mul_f32_e32 v21, 0x37800000, v20
	v_cndmask_b32_e32 v20, v20, v21, vcc
	v_cmp_class_f32_e32 vcc, v10, v56
	s_waitcnt lgkmcnt(0)
	v_add_f32_e32 v7, v7, v22
	ds_bpermute_b32 v22, v48, v7
	v_cndmask_b32_e32 v10, v20, v10, vcc
	v_div_scale_f32 v20, s[4:5], v10, v10, 1.0
	v_rcp_f32_e32 v21, v20
	s_waitcnt lgkmcnt(0)
; __device__ __forceinline__ unsigned cvt_pk_bf16(float lo, float hi) { unsigned r; asm volatile("v_cvt_pk_bf16_f32 %0, %1, %2" : "=v"(r) : "v"(lo), "v"(hi)); return r; }
; __device__ __forceinline__ float bf_lo(unsigned w) { return __uint_as_float(w << 16); }
; __device__ __forceinline__ float bf_hi(unsigned w) { return __uint_as_float(w & 0xffff0000u); }
; __device__ __forceinline__ void combine_row(int row, const float (&y)[8], const float* SSQNA, bf16_t* YCAT, int lane) {
;     float s = 0.f;
; #pragma unroll
;     for (int j = 0; j < 8; ++j) s += y[j] * y[j];
;     s = wave_sum(s);
;     const float rstd = 1.0f / sqrtf(s * (1.0f / 512.0f) + EPS);
;     u32x4 o; o.x = cvt_pk_bf16(y[0] * rstd, y[1] * rstd); o.y = cvt_pk_bf16(y[2] * rstd, y[3] * rstd); o.z = cvt_pk_bf16(y[4] * rstd, y[5] * rstd); o.w = cvt_pk_bf16(y[6] * rstd, y[7] * rstd);
;     *(u32x4*)(YCAT + (size_t)row * DM + lane * 8) = o;
;     float t = SSQNA[(size_t)row * 8 + (lane & 7)]; t += __shfl_xor(t, 1); t += __shfl_xor(t, 2); t += __shfl_xor(t, 4);
;     const float rn = 1.0f / sqrtf(t * (1.0f / 512.0f) + EPS);
;     u32x4* ap = (u32x4*)(YCAT + (size_t)row * DM + 512 + lane * 8); const u32x4 aw = *ap; u32x4 ow;
; #pragma unroll
;     for (int j = 0; j < 4; ++j) ow[j] = cvt_pk_bf16(bf_lo(aw[j]) * rn, bf_hi(aw[j]) * rn);
;     *ap = ow;
; }
; __device__ __forceinline__ void pass_combine(const bf16_t* PQ, const float* SP, const float* XM, const float* SSQNA, bf16_t* YCAT) {
;     ...
;         combine_row(b * SEQ + kk, y1, SSQNA, YCAT, lane);
;         combine_row(b * SEQ + (kk == 0 ? 1024 : SEQ - kk), y2, SSQNA, YCAT, lane);
	v_add_f32_e32 v7, v7, v22
	ds_bpermute_b32 v22, v49, v7
	v_div_scale_f32 v23, s[4:5], 1.0, v10, 1.0
	v_fma_f32 v24, -v20, v21, 1.0
	v_fmac_f32_e32 v21, v24, v21
	s_waitcnt lgkmcnt(0)
	v_add_f32_e32 v7, v7, v22
	v_fmamk_f32 v7, v7, 0x3b000000, v55
	v_mul_f32_e32 v22, 0x4f800000, v7
	v_cmp_gt_f32_e32 vcc, s33, v7
	v_mul_f32_e32 v24, v23, v21
	v_fma_f32 v25, -v20, v24, v23
	v_cndmask_b32_e32 v7, v7, v22, vcc
	v_sqrt_f32_e32 v22, v7
	v_fmac_f32_e32 v24, v25, v21
	v_fma_f32 v20, -v20, v24, v23
	v_lshlrev_b32_e32 v23, 16, v0
	v_add_u32_e32 v28, -1, v22
	v_add_u32_e32 v29, 1, v22
	v_fma_f32 v30, -v28, v22, v7
	v_fma_f32 v31, -v29, v22, v7
	v_cmp_ge_f32_e64 s[6:7], 0, v30
	v_and_b32_e32 v0, 0xffff0000, v0
	v_lshlrev_b32_e32 v25, 16, v1
	v_cndmask_b32_e64 v22, v22, v28, s[6:7]
	v_cmp_lt_f32_e64 s[6:7], 0, v31
	v_and_b32_e32 v1, 0xffff0000, v1
	s_nop 0
	v_cndmask_b32_e64 v22, v22, v29, s[6:7]
	v_mul_f32_e32 v28, 0x37800000, v22
	v_cndmask_b32_e32 v22, v22, v28, vcc
	v_cmp_class_f32_e32 vcc, v7, v56
	s_nop 1
	v_cndmask_b32_e32 v7, v22, v7, vcc
	v_div_scale_f32 v22, s[6:7], v7, v7, 1.0
	v_rcp_f32_e32 v28, v22
	v_div_scale_f32 v29, vcc, 1.0, v7, 1.0
	v_fma_f32 v30, -v22, v28, 1.0
	v_fmac_f32_e32 v28, v30, v28
	v_mul_f32_e32 v30, v29, v28
	v_fma_f32 v31, -v22, v30, v29
	v_fmac_f32_e32 v30, v31, v28
	v_fma_f32 v22, -v22, v30, v29
	v_div_fmas_f32 v22, v22, v28, v30
	s_mov_b64 vcc, s[4:5]
	v_div_fixup_f32 v7, v22, v7, 1.0
	v_div_fmas_f32 v20, v20, v21, v24
	v_mul_f32_e32 v21, v7, v23
	v_mul_f32_e32 v0, v7, v0
	v_mul_f32_e32 v22, v7, v25
	v_mul_f32_e32 v1, v7, v1
	v_mul_f32_e32 v23, v7, v26
	v_mul_f32_e32 v2, v7, v2
	v_mul_f32_e32 v24, v7, v27
	v_mul_f32_e32 v3, v7, v3
	v_div_fixup_f32 v7, v20, v10, 1.0
	v_cvt_pk_bf16_f32 v0, v21, v0
	v_cvt_pk_bf16_f32 v1, v22, v1
	v_cvt_pk_bf16_f32 v2, v23, v2
	v_cvt_pk_bf16_f32 v3, v24, v3
	v_mul_f32_e32 v10, v42, v7
	v_mul_f32_e32 v20, v43, v7
	v_mul_f32_e32 v21, v40, v7
	v_mul_f32_e32 v22, v41, v7
	v_mul_f32_e32 v23, v38, v7
	v_mul_f32_e32 v24, v39, v7
	v_mul_f32_e32 v25, v36, v7
	v_mul_f32_e32 v7, v37, v7
	global_store_dwordx4 v[4:5], v[0:3], off offset:1024 sc1
	s_nop 1
	v_cvt_pk_bf16_f32 v0, v10, v20
	v_cvt_pk_bf16_f32 v1, v21, v22
	v_cvt_pk_bf16_f32 v2, v23, v24
	v_cvt_pk_bf16_f32 v3, v25, v7
	v_ashrrev_i32_e32 v7, 31, v6
	v_lshlrev_b64 v[4:5], 11, v[6:7]
	v_lshl_add_u64 v[4:5], v[16:17], 0, v[4:5]
	global_store_dwordx4 v[4:5], v[0:3], off sc1
	v_add_u32_e32 v10, s10, v9
	v_cmp_lt_i32_e64 s[4:5], s38, v10
	v_lshlrev_b64 v[0:1], 5, v[6:7]
	v_lshl_add_u64 v[0:1], v[14:15], 0, v[0:1]
	global_load_dword v6, v[0:1], off
	s_nop 0
	global_load_dwordx4 v[0:3], v[4:5], off offset:1024 nt
	s_or_b64 s[20:21], s[4:5], s[20:21]
	s_waitcnt vmcnt(1)
	ds_bpermute_b32 v7, v47, v6
	s_waitcnt vmcnt(0)
	v_lshlrev_b32_e32 v10, 16, v0
	v_and_b32_e32 v0, 0xffff0000, v0
	v_lshlrev_b32_e32 v20, 16, v1
	v_and_b32_e32 v1, 0xffff0000, v1
	s_waitcnt lgkmcnt(0)
	v_add_f32_e32 v6, v6, v7
	ds_bpermute_b32 v7, v48, v6
	v_lshlrev_b32_e32 v21, 16, v2
	v_and_b32_e32 v2, 0xffff0000, v2
	v_lshlrev_b32_e32 v22, 16, v3
	v_and_b32_e32 v3, 0xffff0000, v3
	s_waitcnt lgkmcnt(0)
	v_add_f32_e32 v6, v6, v7
	ds_bpermute_b32 v7, v49, v6
	s_waitcnt lgkmcnt(0)
	v_add_f32_e32 v6, v6, v7
	v_fmamk_f32 v6, v6, 0x3b000000, v55
	v_mul_f32_e32 v7, 0x4f800000, v6
	v_cmp_gt_f32_e32 vcc, s33, v6
	s_nop 1
	v_cndmask_b32_e32 v6, v6, v7, vcc
	v_sqrt_f32_e32 v7, v6
	s_nop 0
	v_add_u32_e32 v23, -1, v7
	v_add_u32_e32 v24, 1, v7
	v_fma_f32 v25, -v23, v7, v6
	v_fma_f32 v26, -v24, v7, v6
	v_cmp_ge_f32_e64 s[6:7], 0, v25
	s_nop 1
	v_cndmask_b32_e64 v7, v7, v23, s[6:7]
	v_cmp_lt_f32_e64 s[6:7], 0, v26
	s_nop 1
	v_cndmask_b32_e64 v7, v7, v24, s[6:7]
	v_mul_f32_e32 v23, 0x37800000, v7
	v_cndmask_b32_e32 v7, v7, v23, vcc
	v_cmp_class_f32_e32 vcc, v6, v56
	s_nop 1
	v_cndmask_b32_e32 v6, v7, v6, vcc
	v_div_scale_f32 v7, s[6:7], v6, v6, 1.0
	v_rcp_f32_e32 v23, v7
	v_div_scale_f32 v24, vcc, 1.0, v6, 1.0
	v_fma_f32 v25, -v7, v23, 1.0
	v_fmac_f32_e32 v23, v25, v23
	v_mul_f32_e32 v25, v24, v23
	v_fma_f32 v26, -v7, v25, v24
	v_fmac_f32_e32 v25, v26, v23
	v_fma_f32 v7, -v7, v25, v24
	v_div_fmas_f32 v7, v7, v23, v25
	v_div_fixup_f32 v6, v7, v6, 1.0
	v_mul_f32_e32 v0, v6, v0
	v_mul_f32_e32 v1, v6, v1
	v_mul_f32_e32 v2, v6, v2
	v_mul_f32_e32 v3, v6, v3
	v_mul_f32_e32 v7, v6, v10
	v_mul_f32_e32 v10, v6, v20
	v_mul_f32_e32 v20, v6, v21
	v_mul_f32_e32 v21, v6, v22
	v_cvt_pk_bf16_f32 v0, v7, v0
	v_cvt_pk_bf16_f32 v1, v10, v1
	v_cvt_pk_bf16_f32 v2, v20, v2
	v_cvt_pk_bf16_f32 v3, v21, v3
	global_store_dwordx4 v[4:5], v[0:3], off offset:1024 sc1
	s_andn2_b64 exec, exec, s[20:21]
	s_cbranch_execz .LBB0_411

; __device__ __forceinline__ float bf_lo(unsigned w) { return __uint_as_float(w << 16); }
; __device__ __forceinline__ float bf_hi(unsigned w) { return __uint_as_float(w & 0xffff0000u); }
; __device__ __forceinline__ void pass_combine(const bf16_t* PQ, const float* SP, const float* XM, const float* SSQNA, bf16_t* YCAT) {
;     ...
;     for (int pi0 = gw; pi0 < NBATCH * 1024; pi0 += NGW) {
;         const int pi = (NGW == 2048) ? gw * 4 + (pi0 - gw) / NGW : pi0;
;         const int b = pi >> 10, kk = pi & 1023;
;         const u32x4 pw = *(const u32x4*)(PQ + (size_t)kk * 4096 + b * 512 + lane * 8), qw = *(const u32x4*)(PQ + (size_t)(1024 + kk) * 4096 + b * 512 + lane * 8);
;         float y1[8], y2[8];
;         const f32x4 xa = *(const f32x4*)(XM + b * 512 + lane * 8), xb = *(const f32x4*)(XM + b * 512 + lane * 8 + 4); const float xs = (kk & 1) ? -0.022097086912079608f : 0.022097086912079608f;
;         const float xm[8] = {xa[0] * xs, xa[1] * xs, xa[2] * xs, xa[3] * xs, xb[0] * xs, xb[1] * xs, xb[2] * xs, xb[3] * xs};
; #pragma unroll
;         for (int j = 0; j < 4; ++j) { const float pl = bf_lo(pw[j]) + xm[2 * j], ph = bf_hi(pw[j]) + xm[2 * j + 1], ql = bf_lo(qw[j]), qh = bf_hi(qw[j]); y1[2 * j] = pl - ql; y1[2 * j + 1] = ph - qh; y2[2 * j] = pl + ql; y2[2 * j + 1] = ph + qh; }
;         if (kk == 0) {
; #pragma unroll
;             for (int j = 0; j < 8; ++j) { const f32x4* sp = (const f32x4*)(SP + (size_t)(b * 512 + lane * 8 + j) * 32); f32x4 a = sp[0];
; #pragma unroll
;                 for (int i = 1; i < 4; ++i) a += sp[i];
;                 y2[j] = ((a[0] + a[1]) + (a[2] + a[3])) * 0.022097086912079608f + xm[j]; }
.LBB0_409:
	v_ashrrev_i32_e32 v59, 10, v20
	v_and_b32_e32 v58, 0x3ff, v20
	v_lshlrev_b32_e32 v10, 13, v58
	v_lshlrev_b32_e32 v44, 9, v59
	v_lshl_add_u64 v[0:1], s[14:15], 0, v[10:11]
	v_ashrrev_i32_e32 v45, 31, v44
	v_lshl_add_u64 v[0:1], v[44:45], 1, v[0:1]
	v_lshl_add_u64 v[26:27], v[0:1], 0, v[18:19]
	global_load_dwordx4 v[22:25], v[26:27], off nt
	v_add_co_u32_e32 v26, vcc, s27, v26
	v_lshl_add_u64 v[28:29], v[44:45], 2, v[12:13]
	s_nop 0
	v_addc_co_u32_e32 v27, vcc, 0, v27, vcc
	global_load_dwordx4 v[0:3], v[28:29], off offset:16 nt
	global_load_dwordx4 v[4:7], v[28:29], off nt
	global_load_dwordx4 v[32:35], v[26:27], off nt
	v_and_b32_e32 v10, 1, v20
	v_cmp_eq_u32_e32 vcc, 0, v10
	v_cmp_eq_u32_e64 s[4:5], 0, v58
	s_waitcnt vmcnt(0)
	v_lshlrev_b32_e32 v20, 16, v22
	v_cndmask_b32_e32 v10, v53, v54, vcc
	v_and_b32_e32 v21, 0xffff0000, v22
	v_lshlrev_b32_e32 v22, 16, v23
	v_and_b32_e32 v23, 0xffff0000, v23
	v_lshlrev_b32_e32 v26, 16, v24
	v_and_b32_e32 v27, 0xffff0000, v24
	v_lshlrev_b32_e32 v28, 16, v25
	v_and_b32_e32 v29, 0xffff0000, v25
	v_pk_fma_f32 v[20:21], v[10:11], v[4:5], v[20:21] op_sel_hi:[0,1,1]
	v_pk_fma_f32 v[22:23], v[10:11], v[6:7], v[22:23] op_sel_hi:[0,1,1]
	v_pk_fma_f32 v[24:25], v[10:11], v[0:1], v[26:27] op_sel_hi:[0,1,1]
	v_pk_fma_f32 v[26:27], v[10:11], v[2:3], v[28:29] op_sel_hi:[0,1,1]
	v_lshlrev_b32_e32 v28, 16, v32
	v_and_b32_e32 v29, 0xffff0000, v32
	v_lshlrev_b32_e32 v30, 16, v33
	v_and_b32_e32 v31, 0xffff0000, v33
	v_lshlrev_b32_e32 v32, 16, v34
	v_and_b32_e32 v33, 0xffff0000, v34
	v_lshlrev_b32_e32 v34, 16, v35
	v_and_b32_e32 v35, 0xffff0000, v35
	v_pk_add_f32 v[42:43], v[20:21], v[28:29]
	v_pk_add_f32 v[40:41], v[22:23], v[30:31]
	v_pk_add_f32 v[38:39], v[24:25], v[32:33]
	v_pk_add_f32 v[36:37], v[26:27], v[34:35]
	s_and_saveexec_b64 s[6:7], s[4:5]
	s_cbranch_execz .LBB0_405
	v_or_b32_e32 v44, v44, v8
	v_ashrrev_i32_e32 v45, 31, v44
	v_or_b32_e32 v64, 1, v44
	v_lshlrev_b64 v[36:37], 7, v[44:45]
	v_ashrrev_i32_e32 v65, 31, v64
	v_lshl_add_u64 v[80:81], s[16:17], 0, v[36:37]
	v_lshlrev_b64 v[64:65], 7, v[64:65]
	v_or_b32_e32 v72, 2, v44
	global_load_dwordx4 v[36:39], v[80:81], off offset:32 nt
	global_load_dwordx4 v[40:43], v[80:81], off nt
	global_load_dwordx4 v[60:63], v[80:81], off offset:16 nt
	v_lshl_add_u64 v[88:89], s[16:17], 0, v[64:65]
	v_ashrrev_i32_e32 v73, 31, v72
	global_load_dwordx4 v[64:67], v[88:89], off nt
	global_load_dwordx4 v[68:71], v[88:89], off offset:16 nt
	v_lshlrev_b64 v[72:73], 7, v[72:73]
	v_lshl_add_u64 v[96:97], s[16:17], 0, v[72:73]
	global_load_dwordx4 v[72:75], v[96:97], off nt
	global_load_dwordx4 v[76:79], v[96:97], off offset:16 nt
	s_nop 0
	global_load_dwordx4 v[80:83], v[80:81], off offset:48 nt
	s_nop 0
	global_load_dwordx4 v[84:87], v[88:89], off offset:32 nt
	s_nop 0
	global_load_dwordx4 v[88:91], v[88:89], off offset:48 nt
	v_or_b32_e32 v100, 3, v44
	v_ashrrev_i32_e32 v101, 31, v100
	global_load_dwordx4 v[92:95], v[96:97], off offset:48 nt
	s_nop 0
	global_load_dwordx4 v[96:99], v[96:97], off offset:32 nt
	v_lshlrev_b64 v[100:101], 7, v[100:101]
	v_lshl_add_u64 v[112:113], s[16:17], 0, v[100:101]
	global_load_dwordx4 v[100:103], v[112:113], off nt
	global_load_dwordx4 v[104:107], v[112:113], off offset:16 nt
	global_load_dwordx4 v[108:111], v[112:113], off offset:32 nt
	s_nop 0
	global_load_dwordx4 v[112:115], v[112:113], off offset:48 nt
	v_or_b32_e32 v116, 4, v44
	v_or_b32_e32 v132, 5, v44
	v_ashrrev_i32_e32 v117, 31, v116
	v_ashrrev_i32_e32 v133, 31, v132
	v_lshlrev_b64 v[116:117], 7, v[116:117]
	v_lshl_add_u64 v[128:129], s[16:17], 0, v[116:117]
	v_lshlrev_b64 v[132:133], 7, v[132:133]
	global_load_dwordx4 v[116:119], v[128:129], off nt
	global_load_dwordx4 v[120:123], v[128:129], off offset:16 nt
	global_load_dwordx4 v[124:127], v[128:129], off offset:48 nt
	s_nop 0
	global_load_dwordx4 v[128:131], v[128:129], off offset:32 nt
	v_lshl_add_u64 v[144:145], s[16:17], 0, v[132:133]
	global_load_dwordx4 v[132:135], v[144:145], off nt
	global_load_dwordx4 v[136:139], v[144:145], off offset:16 nt
	global_load_dwordx4 v[140:143], v[144:145], off offset:32 nt
	s_nop 0
	global_load_dwordx4 v[144:147], v[144:145], off offset:48 nt
	v_or_b32_e32 v148, 6, v44
	v_or_b32_e32 v44, 7, v44
	v_ashrrev_i32_e32 v149, 31, v148
	v_ashrrev_i32_e32 v45, 31, v44
	v_lshlrev_b64 v[148:149], 7, v[148:149]
	v_lshlrev_b64 v[44:45], 7, v[44:45]
	v_lshl_add_u64 v[160:161], s[16:17], 0, v[148:149]
	v_lshl_add_u64 v[44:45], s[16:17], 0, v[44:45]
	global_load_dwordx4 v[148:151], v[160:161], off nt
	global_load_dwordx4 v[152:155], v[160:161], off offset:16 nt
	global_load_dwordx4 v[156:159], v[160:161], off offset:48 nt
	s_nop 0
	global_load_dwordx4 v[160:163], v[160:161], off offset:32 nt
	s_nop 0
	global_load_dwordx4 v[164:167], v[44:45], off nt
	global_load_dwordx4 v[172:175], v[44:45], off offset:16 nt
	global_load_dwordx4 v[176:179], v[44:45], off offset:32 nt
	global_load_dwordx4 v[180:183], v[44:45], off offset:48 nt
	v_pk_mul_f32 v[4:5], v[10:11], v[4:5] op_sel_hi:[0,1]
	v_pk_mul_f32 v[6:7], v[10:11], v[6:7] op_sel_hi:[0,1]
	v_pk_mul_f32 v[0:1], v[10:11], v[0:1] op_sel_hi:[0,1]
	v_pk_mul_f32 v[2:3], v[10:11], v[2:3] op_sel_hi:[0,1]
	s_waitcnt vmcnt(29)
; __device__ __forceinline__ void pass_combine(const bf16_t* PQ, const float* SP, const float* XM, const float* SSQNA, bf16_t* YCAT) {
;     ...
;         if (kk == 0) {
; #pragma unroll
;             for (int j = 0; j < 8; ++j) { const f32x4* sp = (const f32x4*)(SP + (size_t)(b * 512 + lane * 8 + j) * 32); f32x4 a = sp[0];
; #pragma unroll
;                 for (int i = 1; i < 4; ++i) a += sp[i];
;                 y2[j] = ((a[0] + a[1]) + (a[2] + a[3])) * 0.022097086912079608f + xm[j]; }
;         }
	v_pk_add_f32 v[42:43], v[42:43], v[62:63]
	v_pk_add_f32 v[40:41], v[40:41], v[60:61]
	v_pk_add_f32 v[38:39], v[42:43], v[38:39]
	s_waitcnt vmcnt(27)
	v_pk_add_f32 v[42:43], v[64:65], v[68:69]
	v_pk_add_f32 v[36:37], v[40:41], v[36:37]
	v_pk_add_f32 v[40:41], v[66:67], v[70:71]
	s_waitcnt vmcnt(23)
	v_pk_add_f32 v[42:43], v[42:43], v[84:85]
	v_pk_add_f32 v[36:37], v[36:37], v[80:81]
	v_pk_add_f32 v[40:41], v[40:41], v[86:87]
	s_waitcnt vmcnt(22)
	v_pk_add_f32 v[42:43], v[42:43], v[88:89]
	v_pk_add_f32 v[60:61], v[72:73], v[76:77]
	v_pk_add_f32 v[38:39], v[38:39], v[82:83]
	v_pk_add_f32 v[40:41], v[40:41], v[90:91]
	v_mov_b32_e32 v62, v36
	v_mov_b32_e32 v63, v42
	v_mov_b32_e32 v42, v37
	v_pk_add_f32 v[44:45], v[74:75], v[78:79]
	v_mov_b32_e32 v36, v38
	v_mov_b32_e32 v37, v40
	v_mov_b32_e32 v40, v39
	v_pk_add_f32 v[38:39], v[62:63], v[42:43]
	s_waitcnt vmcnt(20)
	v_pk_add_f32 v[42:43], v[60:61], v[96:97]
	s_waitcnt vmcnt(18)
	v_pk_add_f32 v[60:61], v[100:101], v[104:105]
	v_pk_add_f32 v[36:37], v[36:37], v[40:41]
	v_pk_add_f32 v[40:41], v[44:45], v[98:99]
	v_pk_add_f32 v[44:45], v[102:103], v[106:107]
	s_waitcnt vmcnt(17)
	v_pk_add_f32 v[60:61], v[60:61], v[108:109]
	v_pk_add_f32 v[42:43], v[42:43], v[92:93]
	v_pk_add_f32 v[44:45], v[44:45], v[110:111]
	s_waitcnt vmcnt(16)
	v_pk_add_f32 v[60:61], v[60:61], v[112:113]
	v_pk_add_f32 v[40:41], v[40:41], v[94:95]
	v_pk_add_f32 v[44:45], v[44:45], v[114:115]
	v_mov_b32_e32 v62, v42
	v_mov_b32_e32 v63, v60
	v_mov_b32_e32 v60, v43
	v_pk_add_f32 v[42:43], v[62:63], v[60:61]
	v_mov_b32_e32 v60, v40
	v_mov_b32_e32 v61, v44
	v_mov_b32_e32 v44, v41
	v_pk_add_f32 v[40:41], v[60:61], v[44:45]
	s_waitcnt vmcnt(14)
	v_pk_add_f32 v[60:61], v[116:117], v[120:121]
	s_waitcnt vmcnt(10)
	v_pk_add_f32 v[64:65], v[132:133], v[136:137]
	v_pk_add_f32 v[60:61], v[60:61], v[128:129]
	s_waitcnt vmcnt(9)
	v_pk_add_f32 v[64:65], v[64:65], v[140:141]
	v_pk_add_f32 v[44:45], v[118:119], v[122:123]
	v_pk_add_f32 v[60:61], v[60:61], v[124:125]
	v_pk_add_f32 v[62:63], v[134:135], v[138:139]
	s_waitcnt vmcnt(8)
	v_pk_add_f32 v[64:65], v[64:65], v[144:145]
	v_pk_add_f32 v[44:45], v[44:45], v[130:131]
	v_pk_add_f32 v[62:63], v[62:63], v[142:143]
	v_mov_b32_e32 v66, v60
	v_mov_b32_e32 v67, v64
	v_mov_b32_e32 v64, v61
	v_pk_add_f32 v[44:45], v[44:45], v[126:127]
	v_pk_add_f32 v[62:63], v[62:63], v[146:147]
	v_pk_add_f32 v[60:61], v[66:67], v[64:65]
	s_waitcnt vmcnt(2)
	v_pk_add_f32 v[66:67], v[166:167], v[174:175]
	v_pk_add_f32 v[68:69], v[164:165], v[172:173]
	v_mov_b32_e32 v64, v44
	v_mov_b32_e32 v65, v62
	v_mov_b32_e32 v62, v45
	s_waitcnt vmcnt(1)
	v_pk_add_f32 v[66:67], v[66:67], v[178:179]
	v_pk_add_f32 v[68:69], v[68:69], v[176:177]
	v_pk_add_f32 v[44:45], v[64:65], v[62:63]
	v_pk_add_f32 v[62:63], v[150:151], v[154:155]
	v_pk_add_f32 v[64:65], v[148:149], v[152:153]
	s_waitcnt vmcnt(0)
	v_pk_add_f32 v[66:67], v[66:67], v[182:183]
	v_pk_add_f32 v[68:69], v[68:69], v[180:181]
	v_pk_add_f32 v[62:63], v[62:63], v[162:163]
	v_pk_add_f32 v[64:65], v[64:65], v[160:161]
	v_pk_mov_b32 v[70:71], v[68:69], v[66:67] op_sel:[1,0]
	v_mov_b32_e32 v69, v67
	v_pk_add_f32 v[62:63], v[62:63], v[158:159]
	v_pk_add_f32 v[64:65], v[64:65], v[156:157]
	v_pk_add_f32 v[66:67], v[70:71], v[68:69]
	v_add_f32_e32 v64, v64, v65
	v_add_f32_e32 v62, v62, v63
	v_mov_b32_e32 v65, v66
	v_mov_b32_e32 v63, v67
	v_pk_add_f32 v[66:67], v[38:39], v[36:37]
	v_pk_add_f32 v[40:41], v[42:43], v[40:41]
	v_pk_add_f32 v[38:39], v[60:61], v[44:45]
	v_pk_add_f32 v[36:37], v[64:65], v[62:63]
	v_pk_fma_f32 v[38:39], v[38:39], s[26:27], v[0:1] op_sel_hi:[1,0,1]
	v_pk_fma_f32 v[36:37], v[36:37], s[26:27], v[2:3] op_sel_hi:[1,0,1]
	v_pk_fma_f32 v[40:41], v[40:41], s[26:27], v[6:7] op_sel_hi:[1,0,1]
	v_pk_fma_f32 v[42:43], v[66:67], s[26:27], v[4:5] op_sel_hi:[1,0,1]
	s_branch .LBB0_405

; __device__ __forceinline__ float bf_lo(unsigned w) { return __uint_as_float(w << 16); }
; __device__ __forceinline__ float bf_hi(unsigned w) { return __uint_as_float(w & 0xffff0000u); }
;     __device__ __forceinline__ void fused(f32x4 (&acc)[2][2][4][2], const Unit& u, int wr, int wc, int fr, int fq, LAS unsigned char* lds, int wid, int lane) const {
;         const int row0 = u.pm * BM + wr * 64 + fr, col0 = u.pn * BM + wc * 32 + 4 * fq, b = u.pm >> 3;
;         const float* modb = mod + (size_t)b * NMOD + col0;
;         { f32x4 gv[2][2];
; #pragma unroll
;           for (int bj = 0; bj < 2; ++bj)
; #pragma unroll
;             for (int n = 0; n < 2; ++n) gv[bj][n] = *(const f32x4*)(modb + gate_off + bj * HALF + n * 16);
; #pragma unroll
;           for (int ai = 0; ai < 2; ++ai)
; #pragma unroll
;             for (int m = 0; m < 4; ++m) { const size_t off = (size_t)(row0 + ai * HALF + m * 16) * DM + col0;
; #pragma unroll
;                 for (int bj = 0; bj < 2; ++bj)
; #pragma unroll
;                     for (int n = 0; n < 2; ++n) { const u32x2 xw = *(const u32x2*)(x1b + off + bj * HALF + n * 16); const f32x4 xv = (f32x4){bf_lo(xw.x), bf_hi(xw.x), bf_lo(xw.y), bf_hi(xw.y)};
;                         acc[ai][bj][m][n] = xv + gv[bj][n] * acc[ai][bj][m][n]; }
;                 asm volatile("" : "+v"(acc[ai][0][m][0]), "+v"(acc[ai][0][m][1]), "+v"(acc[ai][1][m][0]), "+v"(acc[ai][1][m][1]));
;                 asm volatile("" ::: "memory"); } }
.LBB0_1125:
	s_add_u32 s0, s34, 0xd200000
	s_addc_u32 s1, s35, 0
	s_lshl_b32 s11, s45, 5
	s_lshl_b32 s10, s43, 8
	s_lshl_b32 s13, s8, 8
	s_add_i32 s12, s10, s50
	s_or_b32 s11, s13, s11
	v_and_or_b32 v144, v136, 12, s11
	v_or_b32_e32 v148, s12, v156
	s_ashr_i32 s11, s43, 3
	v_ashrrev_i32_e32 v149, 31, v148
	s_mul_hi_i32 s13, s11, 0x6000
	s_mulk_i32 s11, 0x6000
	v_ashrrev_i32_e32 v145, 31, v144
	v_lshlrev_b64 v[128:129], 11, v[148:149]
	s_add_u32 s12, s34, s11
	v_lshl_add_u64 v[128:129], s[0:1], 0, v[128:129]
	v_lshlrev_b64 v[150:151], 1, v[144:145]
	s_addc_u32 s13, s35, s13
	v_lshl_add_u64 v[146:147], v[128:129], 0, v[150:151]
	v_lshl_add_u64 v[128:129], v[144:145], 2, s[12:13]
	s_movk_i32 s11, 0x5000
	v_add_co_u32_e32 v128, vcc, s11, v128
	s_barrier
	global_load_dwordx2 v[154:155], v[146:147], off nt
	global_load_dwordx2 v[158:159], v[146:147], off offset:32 nt
	global_load_dwordx2 v[160:161], v[146:147], off offset:256 nt
	global_load_dwordx2 v[162:163], v[146:147], off offset:288 nt
	v_addc_co_u32_e32 v129, vcc, 0, v129, vcc
	global_load_dwordx4 v[140:143], v[128:129], off
	global_load_dwordx4 v[136:139], v[128:129], off offset:64
	global_load_dwordx4 v[132:135], v[128:129], off offset:512
	s_nop 0
	global_load_dwordx4 v[128:131], v[128:129], off offset:576
	v_or_b32_e32 v164, 16, v148
	v_ashrrev_i32_e32 v165, 31, v164
	v_lshlrev_b64 v[164:165], 11, v[164:165]
	v_lshl_add_u64 v[164:165], s[0:1], 0, v[164:165]
	v_lshl_add_u64 v[164:165], v[164:165], 0, v[150:151]
	s_waitcnt vmcnt(0)
	v_lshlrev_b32_e32 v166, 16, v154
	v_and_b32_e32 v167, 0xffff0000, v154
	v_lshlrev_b32_e32 v154, 16, v155
	v_and_b32_e32 v155, 0xffff0000, v155
	v_lshlrev_b32_e32 v168, 16, v158
	v_and_b32_e32 v169, 0xffff0000, v158
	v_lshlrev_b32_e32 v158, 16, v159
	v_and_b32_e32 v159, 0xffff0000, v159
	v_lshlrev_b32_e32 v172, 16, v160
	v_and_b32_e32 v173, 0xffff0000, v160
	v_lshlrev_b32_e32 v160, 16, v161
	v_and_b32_e32 v161, 0xffff0000, v161
	v_lshlrev_b32_e32 v174, 16, v162
	v_and_b32_e32 v175, 0xffff0000, v162
	v_lshlrev_b32_e32 v162, 16, v163
	v_and_b32_e32 v163, 0xffff0000, v163
	v_pk_fma_f32 v[120:121], v[120:121], v[140:141], v[166:167]
	v_pk_fma_f32 v[122:123], v[122:123], v[142:143], v[154:155]
	v_pk_fma_f32 v[124:125], v[124:125], v[136:137], v[168:169]
	v_pk_fma_f32 v[126:127], v[126:127], v[138:139], v[158:159]
	v_pk_fma_f32 v[116:117], v[116:117], v[132:133], v[172:173]
	v_pk_fma_f32 v[118:119], v[118:119], v[134:135], v[160:161]
	v_pk_fma_f32 v[112:113], v[112:113], v[128:129], v[174:175]
	v_pk_fma_f32 v[114:115], v[114:115], v[130:131], v[162:163]
	s_nop 0
	global_load_dwordx2 v[154:155], v[164:165], off nt
	global_load_dwordx2 v[158:159], v[164:165], off offset:32 nt
	global_load_dwordx2 v[160:161], v[164:165], off offset:256 nt
	global_load_dwordx2 v[162:163], v[164:165], off offset:288 nt
	v_or_b32_e32 v164, 32, v148
	v_ashrrev_i32_e32 v165, 31, v164
	v_lshlrev_b64 v[164:165], 11, v[164:165]
	v_lshl_add_u64 v[164:165], s[0:1], 0, v[164:165]
	v_lshl_add_u64 v[164:165], v[164:165], 0, v[150:151]
	v_or_b32_e32 v148, 48, v148
	v_ashrrev_i32_e32 v149, 31, v148
	v_lshlrev_b64 v[148:149], 11, v[148:149]
	v_lshl_add_u64 v[148:149], s[0:1], 0, v[148:149]
	v_lshl_add_u64 v[148:149], v[148:149], 0, v[150:151]
	s_mov_b32 s0, 0x40000
	v_mul_f32_e32 v153, v125, v125
	v_mul_f32_e32 v157, v127, v127
	v_fmac_f32_e32 v153, v124, v124
	v_fmac_f32_e32 v157, v126, v126
	s_waitcnt vmcnt(0)
	v_lshlrev_b32_e32 v166, 16, v154
	v_and_b32_e32 v167, 0xffff0000, v154
	v_lshlrev_b32_e32 v154, 16, v155
	v_and_b32_e32 v155, 0xffff0000, v155
	v_lshlrev_b32_e32 v168, 16, v158
	v_and_b32_e32 v169, 0xffff0000, v158
	v_lshlrev_b32_e32 v158, 16, v159
	v_and_b32_e32 v159, 0xffff0000, v159
	v_lshlrev_b32_e32 v172, 16, v160
	v_and_b32_e32 v173, 0xffff0000, v160
	v_lshlrev_b32_e32 v160, 16, v161
	v_and_b32_e32 v161, 0xffff0000, v161
	v_lshlrev_b32_e32 v174, 16, v162
	v_and_b32_e32 v175, 0xffff0000, v162
	v_lshlrev_b32_e32 v162, 16, v163
	v_and_b32_e32 v163, 0xffff0000, v163
	v_pk_fma_f32 v[110:111], v[110:111], v[142:143], v[154:155]
	v_pk_fma_f32 v[108:109], v[108:109], v[140:141], v[166:167]
	v_pk_fma_f32 v[106:107], v[106:107], v[138:139], v[158:159]
	v_pk_fma_f32 v[104:105], v[104:105], v[136:137], v[168:169]
	v_pk_fma_f32 v[102:103], v[102:103], v[134:135], v[160:161]
	v_pk_fma_f32 v[100:101], v[100:101], v[132:133], v[172:173]
	v_pk_fma_f32 v[98:99], v[98:99], v[130:131], v[162:163]
	v_pk_fma_f32 v[96:97], v[96:97], v[128:129], v[174:175]
	s_nop 0
	global_load_dwordx2 v[154:155], v[164:165], off nt
	global_load_dwordx2 v[158:159], v[164:165], off offset:32 nt
	global_load_dwordx2 v[160:161], v[164:165], off offset:256 nt
	global_load_dwordx2 v[162:163], v[164:165], off offset:288 nt
	s_waitcnt vmcnt(0)
	v_lshlrev_b32_e32 v150, 16, v154
	v_and_b32_e32 v151, 0xffff0000, v154
	v_lshlrev_b32_e32 v154, 16, v155
	v_and_b32_e32 v155, 0xffff0000, v155
	v_lshlrev_b32_e32 v164, 16, v158
	v_and_b32_e32 v165, 0xffff0000, v158
	v_lshlrev_b32_e32 v158, 16, v159
	v_and_b32_e32 v159, 0xffff0000, v159
	v_lshlrev_b32_e32 v166, 16, v160
	v_and_b32_e32 v167, 0xffff0000, v160
	v_lshlrev_b32_e32 v160, 16, v161
	v_and_b32_e32 v161, 0xffff0000, v161
	v_lshlrev_b32_e32 v168, 16, v162
	v_and_b32_e32 v169, 0xffff0000, v162
	v_lshlrev_b32_e32 v162, 16, v163
	v_and_b32_e32 v163, 0xffff0000, v163
	v_pk_fma_f32 v[94:95], v[94:95], v[142:143], v[154:155]
	v_pk_fma_f32 v[92:93], v[92:93], v[140:141], v[150:151]
	v_pk_fma_f32 v[90:91], v[90:91], v[138:139], v[158:159]
	v_pk_fma_f32 v[88:89], v[88:89], v[136:137], v[164:165]
	v_pk_fma_f32 v[86:87], v[86:87], v[134:135], v[160:161]
	v_pk_fma_f32 v[84:85], v[84:85], v[132:133], v[166:167]
	v_pk_fma_f32 v[82:83], v[82:83], v[130:131], v[162:163]
	v_pk_fma_f32 v[80:81], v[80:81], v[128:129], v[168:169]
	v_add_co_u32_e32 v160, vcc, s0, v146
	global_load_dwordx2 v[150:151], v[148:149], off nt
	global_load_dwordx2 v[154:155], v[148:149], off offset:32 nt
	global_load_dwordx2 v[158:159], v[148:149], off offset:256 nt
	s_nop 0
	global_load_dwordx2 v[148:149], v[148:149], off offset:288 nt
	s_mov_b64 s[0:1], 0x40000
	v_addc_co_u32_e32 v161, vcc, 0, v147, vcc
	s_waitcnt vmcnt(0)
; __device__ __forceinline__ float bf_lo(unsigned w) { return __uint_as_float(w << 16); }
; __device__ __forceinline__ float bf_hi(unsigned w) { return __uint_as_float(w & 0xffff0000u); }
;     __device__ __forceinline__ void fused(f32x4 (&acc)[2][2][4][2], const Unit& u, int wr, int wc, int fr, int fq, LAS unsigned char* lds, int wid, int lane) const {
;     ...
;             for (int m = 0; m < 4; ++m) { const size_t off = (size_t)(row0 + ai * HALF + m * 16) * DM + col0;
; #pragma unroll
;                 for (int bj = 0; bj < 2; ++bj)
; #pragma unroll
;                     for (int n = 0; n < 2; ++n) { const u32x2 xw = *(const u32x2*)(x1b + off + bj * HALF + n * 16); const f32x4 xv = (f32x4){bf_lo(xw.x), bf_hi(xw.x), bf_lo(xw.y), bf_hi(xw.y)};
;                         acc[ai][bj][m][n] = xv + gv[bj][n] * acc[ai][bj][m][n]; }
;                 asm volatile("" : "+v"(acc[ai][0][m][0]), "+v"(acc[ai][0][m][1]), "+v"(acc[ai][1][m][0]), "+v"(acc[ai][1][m][1]));
;                 asm volatile("" ::: "memory"); } }
	v_lshlrev_b32_e32 v162, 16, v150
	v_and_b32_e32 v163, 0xffff0000, v150
	v_lshlrev_b32_e32 v150, 16, v151
	v_and_b32_e32 v151, 0xffff0000, v151
	v_lshlrev_b32_e32 v164, 16, v154
	v_and_b32_e32 v165, 0xffff0000, v154
	v_lshlrev_b32_e32 v154, 16, v155
	v_and_b32_e32 v155, 0xffff0000, v155
	v_lshlrev_b32_e32 v166, 16, v158
	v_and_b32_e32 v167, 0xffff0000, v158
	v_lshlrev_b32_e32 v158, 16, v159
	v_and_b32_e32 v159, 0xffff0000, v159
	v_lshlrev_b32_e32 v168, 16, v148
	v_and_b32_e32 v169, 0xffff0000, v148
	v_lshlrev_b32_e32 v148, 16, v149
	v_and_b32_e32 v149, 0xffff0000, v149
	v_pk_fma_f32 v[78:79], v[78:79], v[142:143], v[150:151]
	v_pk_fma_f32 v[76:77], v[76:77], v[140:141], v[162:163]
	v_pk_fma_f32 v[74:75], v[74:75], v[138:139], v[154:155]
	v_pk_fma_f32 v[72:73], v[72:73], v[136:137], v[164:165]
	v_pk_fma_f32 v[70:71], v[70:71], v[134:135], v[158:159]
	v_pk_fma_f32 v[68:69], v[68:69], v[132:133], v[166:167]
	v_pk_fma_f32 v[66:67], v[66:67], v[130:131], v[148:149]
	v_pk_fma_f32 v[64:65], v[64:65], v[128:129], v[168:169]
	v_lshl_add_u64 v[150:151], v[146:147], 0, s[0:1]
	global_load_dwordx2 v[148:149], v[160:161], off nt
	global_load_dwordx2 v[154:155], v[150:151], off offset:32 nt
	global_load_dwordx2 v[158:159], v[150:151], off offset:256 nt
	s_nop 0
	global_load_dwordx2 v[150:151], v[150:151], off offset:288 nt
	s_mov_b32 s0, 0x48000
	v_add_co_u32_e32 v160, vcc, s0, v146
	s_mov_b64 s[0:1], 0x48000
	s_nop 0
	v_addc_co_u32_e32 v161, vcc, 0, v147, vcc
	s_waitcnt vmcnt(0)
	v_lshlrev_b32_e32 v164, 16, v154
	v_lshlrev_b32_e32 v162, 16, v148
	v_and_b32_e32 v163, 0xffff0000, v148
	v_lshlrev_b32_e32 v148, 16, v149
	v_and_b32_e32 v149, 0xffff0000, v149
	v_and_b32_e32 v165, 0xffff0000, v154
	v_lshlrev_b32_e32 v154, 16, v155
	v_and_b32_e32 v155, 0xffff0000, v155
	v_lshlrev_b32_e32 v166, 16, v158
	v_and_b32_e32 v167, 0xffff0000, v158
	v_lshlrev_b32_e32 v158, 16, v159
	v_and_b32_e32 v159, 0xffff0000, v159
	v_lshlrev_b32_e32 v168, 16, v150
	v_and_b32_e32 v169, 0xffff0000, v150
	v_lshlrev_b32_e32 v150, 16, v151
	v_and_b32_e32 v151, 0xffff0000, v151
	v_pk_fma_f32 v[62:63], v[62:63], v[142:143], v[148:149]
	v_pk_fma_f32 v[60:61], v[60:61], v[140:141], v[162:163]
	v_pk_fma_f32 v[58:59], v[58:59], v[138:139], v[154:155]
	v_pk_fma_f32 v[56:57], v[56:57], v[136:137], v[164:165]
	v_pk_fma_f32 v[54:55], v[54:55], v[134:135], v[158:159]
	v_pk_fma_f32 v[52:53], v[52:53], v[132:133], v[166:167]
	v_pk_fma_f32 v[50:51], v[50:51], v[130:131], v[150:151]
	v_pk_fma_f32 v[48:49], v[48:49], v[128:129], v[168:169]
	v_lshl_add_u64 v[150:151], v[146:147], 0, s[0:1]
	global_load_dwordx2 v[148:149], v[160:161], off nt
	global_load_dwordx2 v[154:155], v[150:151], off offset:32 nt
	global_load_dwordx2 v[158:159], v[150:151], off offset:256 nt
	s_nop 0
	global_load_dwordx2 v[150:151], v[150:151], off offset:288 nt
	s_mov_b32 s0, 0x50000
	v_add_co_u32_e32 v160, vcc, s0, v146
	s_mov_b64 s[0:1], 0x50000
	s_nop 0
	v_addc_co_u32_e32 v161, vcc, 0, v147, vcc
	s_waitcnt vmcnt(0)
	v_lshlrev_b32_e32 v164, 16, v154
	v_lshlrev_b32_e32 v162, 16, v148
	v_and_b32_e32 v163, 0xffff0000, v148
	v_lshlrev_b32_e32 v148, 16, v149
	v_and_b32_e32 v149, 0xffff0000, v149
	v_and_b32_e32 v165, 0xffff0000, v154
	v_lshlrev_b32_e32 v154, 16, v155
	v_and_b32_e32 v155, 0xffff0000, v155
	v_lshlrev_b32_e32 v166, 16, v158
	v_and_b32_e32 v167, 0xffff0000, v158
	v_lshlrev_b32_e32 v158, 16, v159
	v_and_b32_e32 v159, 0xffff0000, v159
	v_lshlrev_b32_e32 v168, 16, v150
	v_and_b32_e32 v169, 0xffff0000, v150
	v_lshlrev_b32_e32 v150, 16, v151
	v_and_b32_e32 v151, 0xffff0000, v151
	v_pk_fma_f32 v[46:47], v[46:47], v[142:143], v[148:149]
	v_pk_fma_f32 v[44:45], v[44:45], v[140:141], v[162:163]
	v_pk_fma_f32 v[42:43], v[42:43], v[138:139], v[154:155]
	v_pk_fma_f32 v[40:41], v[40:41], v[136:137], v[164:165]
	v_pk_fma_f32 v[38:39], v[38:39], v[134:135], v[158:159]
	v_pk_fma_f32 v[36:37], v[36:37], v[132:133], v[166:167]
	v_pk_fma_f32 v[34:35], v[34:35], v[130:131], v[150:151]
	v_pk_fma_f32 v[32:33], v[32:33], v[128:129], v[168:169]
	v_lshl_add_u64 v[150:151], v[146:147], 0, s[0:1]
	global_load_dwordx2 v[148:149], v[160:161], off nt
	global_load_dwordx2 v[154:155], v[150:151], off offset:32 nt
	global_load_dwordx2 v[158:159], v[150:151], off offset:256 nt
	s_nop 0
	global_load_dwordx2 v[150:151], v[150:151], off offset:288 nt
	s_mov_b32 s0, 0x58000
	v_add_co_u32_e32 v160, vcc, s0, v146
	s_mov_b64 s[0:1], 0x58000
	s_nop 0
	v_addc_co_u32_e32 v161, vcc, 0, v147, vcc
	v_lshl_add_u64 v[146:147], v[146:147], 0, s[0:1]
	s_lshl_b32 s0, s45, 2
	s_add_i32 s11, s0, 0
	s_waitcnt vmcnt(0)
; #define LAS __attribute__((address_space(3)))
; __device__ __forceinline__ float bf_lo(unsigned w) { return __uint_as_float(w << 16); }
; __device__ __forceinline__ float bf_hi(unsigned w) { return __uint_as_float(w & 0xffff0000u); }
;     __device__ __forceinline__ void run(const f32x4 (&v)[2][2][4][2], const Unit& u, int wr, int wc, int fr, int fq, LAS unsigned char* lds, int wid, int lane) const {
;         LAS float* P = (LAS float*)lds; LAS float* S = (LAS float*)(lds + 4096);
; #pragma unroll
;         for (int ai = 0; ai < 2; ++ai)
; #pragma unroll
;             for (int m = 0; m < 4; ++m) { float s = 0.f;
; #pragma unroll
;                 for (int bj = 0; bj < 2; ++bj)
; #pragma unroll
;                     for (int n = 0; n < 2; ++n) { const f32x4 x = v[ai][bj][m][n]; s += (x[0] * x[0] + x[1] * x[1]) + (x[2] * x[2] + x[3] * x[3]); }
;                 s += __shfl_xor(s, 16); s += __shfl_xor(s, 32);
;                 if (fq == 0) P[(ai * HALF + wr * 64 + m * 16 + fr) * 4 + wc] = s; }
;     __device__ __forceinline__ void fused(f32x4 (&acc)[2][2][4][2], const Unit& u, int wr, int wc, int fr, int fq, LAS unsigned char* lds, int wid, int lane) const {
;     ...
;                     for (int n = 0; n < 2; ++n) { const u32x2 xw = *(const u32x2*)(x1b + off + bj * HALF + n * 16); const f32x4 xv = (f32x4){bf_lo(xw.x), bf_hi(xw.x), bf_lo(xw.y), bf_hi(xw.y)};
;                         acc[ai][bj][m][n] = xv + gv[bj][n] * acc[ai][bj][m][n]; }
;                 asm volatile("" : "+v"(acc[ai][0][m][0]), "+v"(acc[ai][0][m][1]), "+v"(acc[ai][1][m][0]), "+v"(acc[ai][1][m][1]));
;                 asm volatile("" ::: "memory"); } }
;         st.run(acc, u, wr, wc, fr, fq, lds, wid, lane);
	v_lshlrev_b32_e32 v164, 16, v154
	v_lshlrev_b32_e32 v162, 16, v148
	v_and_b32_e32 v163, 0xffff0000, v148
	v_lshlrev_b32_e32 v148, 16, v149
	v_and_b32_e32 v149, 0xffff0000, v149
	v_and_b32_e32 v165, 0xffff0000, v154
	v_lshlrev_b32_e32 v154, 16, v155
	v_and_b32_e32 v155, 0xffff0000, v155
	v_lshlrev_b32_e32 v166, 16, v158
	v_and_b32_e32 v167, 0xffff0000, v158
	v_lshlrev_b32_e32 v158, 16, v159
	v_and_b32_e32 v159, 0xffff0000, v159
	v_lshlrev_b32_e32 v168, 16, v150
	v_and_b32_e32 v169, 0xffff0000, v150
	v_lshlrev_b32_e32 v150, 16, v151
	v_and_b32_e32 v151, 0xffff0000, v151
	v_pk_fma_f32 v[30:31], v[30:31], v[142:143], v[148:149]
	v_pk_fma_f32 v[28:29], v[28:29], v[140:141], v[162:163]
	v_pk_fma_f32 v[26:27], v[26:27], v[138:139], v[154:155]
	v_pk_fma_f32 v[24:25], v[24:25], v[136:137], v[164:165]
	v_pk_fma_f32 v[22:23], v[22:23], v[134:135], v[158:159]
	v_pk_fma_f32 v[20:21], v[20:21], v[132:133], v[166:167]
	v_pk_fma_f32 v[18:19], v[18:19], v[130:131], v[150:151]
	v_pk_fma_f32 v[16:17], v[16:17], v[128:129], v[168:169]
	v_mul_f32_e32 v150, v121, v121
	global_load_dwordx2 v[154:155], v[160:161], off nt
	global_load_dwordx2 v[158:159], v[146:147], off offset:32 nt
	s_nop 0
	global_load_dwordx2 v[160:161], v[146:147], off offset:256 nt
	global_load_dwordx2 v[162:163], v[146:147], off offset:288 nt
	v_mbcnt_lo_u32_b32 v147, -1, 0
	v_mbcnt_hi_u32_b32 v148, -1, v147
	v_mul_f32_e32 v151, v123, v123
	v_and_b32_e32 v149, 64, v148
	v_mul_f32_e32 v164, v117, v117
	v_mul_f32_e32 v165, v119, v119
	v_fmac_f32_e32 v150, v120, v120
	v_fmac_f32_e32 v151, v122, v122
	v_xor_b32_e32 v147, 16, v148
	v_add_u32_e32 v149, 64, v149
	v_mul_f32_e32 v166, v113, v113
	v_mul_f32_e32 v167, v115, v115
	v_fmac_f32_e32 v164, v116, v116
	v_fmac_f32_e32 v165, v118, v118
	v_add_f32_e32 v150, v150, v151
	v_add_f32_e32 v151, v153, v157
	v_cmp_lt_i32_e32 vcc, v147, v149
	v_fmac_f32_e32 v166, v112, v112
	v_fmac_f32_e32 v167, v114, v114
	v_add_f32_e32 v153, v164, v165
	v_add_f32_e32 v150, v150, v151
	v_cndmask_b32_e32 v147, v148, v147, vcc
	v_add_f32_e32 v157, v166, v167
	v_add_f32_e32 v150, v153, v150
	v_lshlrev_b32_e32 v147, 2, v147
	v_add_f32_e32 v150, v157, v150
	ds_bpermute_b32 v151, v147, v150
	v_xor_b32_e32 v153, 32, v148
	v_cmp_lt_i32_e32 vcc, v153, v149
	v_and_b32_e32 v146, 63, v170
	s_waitcnt lgkmcnt(0)
	v_add_f32_e32 v149, v150, v151
	v_cndmask_b32_e32 v148, v148, v153, vcc
	v_lshlrev_b32_e32 v148, 2, v148
	ds_bpermute_b32 v150, v148, v149
	v_cmp_gt_u32_e32 vcc, 16, v146
	s_waitcnt vmcnt(2)
	v_lshlrev_b32_e32 v166, 16, v158
	v_lshlrev_b32_e32 v164, 16, v154
	v_and_b32_e32 v165, 0xffff0000, v154
	v_lshlrev_b32_e32 v154, 16, v155
	v_and_b32_e32 v155, 0xffff0000, v155
	v_and_b32_e32 v167, 0xffff0000, v158
	v_lshlrev_b32_e32 v158, 16, v159
	v_and_b32_e32 v159, 0xffff0000, v159
	s_waitcnt vmcnt(1)
	v_lshlrev_b32_e32 v168, 16, v160
	v_and_b32_e32 v169, 0xffff0000, v160
	v_lshlrev_b32_e32 v160, 16, v161
	v_and_b32_e32 v161, 0xffff0000, v161
	s_waitcnt vmcnt(0)
	v_lshlrev_b32_e32 v172, 16, v162
	v_and_b32_e32 v173, 0xffff0000, v162
	v_lshlrev_b32_e32 v162, 16, v163
	v_and_b32_e32 v163, 0xffff0000, v163
	v_pk_fma_f32 v[14:15], v[14:15], v[142:143], v[154:155]
	v_pk_fma_f32 v[12:13], v[12:13], v[140:141], v[164:165]
	v_pk_fma_f32 v[10:11], v[10:11], v[138:139], v[158:159]
	v_pk_fma_f32 v[8:9], v[8:9], v[136:137], v[166:167]
	v_pk_fma_f32 v[6:7], v[6:7], v[134:135], v[160:161]
	v_pk_fma_f32 v[4:5], v[4:5], v[132:133], v[168:169]
	v_pk_fma_f32 v[2:3], v[2:3], v[130:131], v[162:163]
	v_pk_fma_f32 v[0:1], v[0:1], v[128:129], v[172:173]
	s_nop 0
	s_and_saveexec_b64 s[0:1], vcc
	v_readlane_b32 s56, v240, 6
	v_readlane_b32 s58, v240, 8
	v_readlane_b32 s57, v240, 7
	v_readlane_b32 s59, v240, 9
	s_cbranch_execz .LBB0_1127
	s_lshl_b32 s12, s44, 10
	s_add_i32 s12, s11, s12
	v_lshl_add_u32 v128, v156, 4, s12
	s_waitcnt lgkmcnt(0)
	v_add_f32_e32 v129, v149, v150
	ds_write_b32 v128, v129
